# strategy 4: mixer phases - one static s_setprio 1 for waves 4-7, the 10 per-cluster flips in the attention tile loops deleted
# baseline (speedup 1.0000x reference)
; #define LAS __attribute__((address_space(3)))
; DI int lane_id_fresh() { unsigned zero; asm volatile("v_mov_b32 %0, 0" : "=v"(zero)); return (int)__builtin_amdgcn_mbcnt_hi(~0u, __builtin_amdgcn_mbcnt_lo(~0u, zero)); }
; #define PHASE_IDS() int lane = lane_id_fresh(); int wave = wave_s; asm volatile("" : "+s"(wave)); \
;         int bid = blockIdx.x; asm volatile("" : "+s"(bid)); int G = gridDim.x; asm volatile("" : "+s"(G)); \
;         const int tid = wave * 64 + lane, gw = bid * NWAVES + wave, NGW = G * NWAVES; (void)tid; (void)gw; (void)NGW
; __global__ void __launch_bounds__(NTHREADS) hybrid_fwd(Params p) {
;     ...
;             LAS float* btab = (LAS float*)(lds + 8 * 14336);
;             for (int idx = tid; idx < 32 * 129; idx += NTHREADS) {
;                 const int hd = idx / 129, d = idx % 129;
;                 int bucket = d;
;                 if (d >= 16) { bucket = 16 + (int)(logf((float)d * (1.0f / 16.0f)) / 2.0794415416798357f * 16.0f); bucket = bucket > 31 ? 31 : bucket; }
;                 btab[idx] = p.rel_bias[bucket * 32 + hd] * 1.4426950408889634f;
;             }
;             __syncthreads();
;             LAS bf16_t* vs = (LAS bf16_t*)(lds + wave * 14336);
;             const float* sinks = p.sinks_a + j * 32;
;             AttnQueue aq{(unsigned*)(p.ws + WS_Q) + layer * 8 * 64, (int)(xb.x & 7u), 0}; int qs, hd;
;             while (attn_next(aq, lane_id_fresh() == 0, qs, hd)) attnA_item(z, sinks, hd, qs == NQS ? -1 : qs, vs, btab, lane_id_fresh());
;         } else {
;             PHASE_IDS();
;             LAS bf16_t* vs = (LAS bf16_t*)(lds + wave * (VS_BYTES + 8192));
.LBB0_128:
	s_mov_b64 s[4:5], -1
	s_and_b64 vcc, exec, s[0:1]
	s_waitcnt lgkmcnt(0)
	s_barrier
	v_readlane_b32 s23, v239, 1
	s_nop 3
	s_cmp_lt_u32 s23, 4
	s_cbranch_scc1 .Lprio_att_done
	s_setprio 1
.Lprio_att_done:
	s_cbranch_vccz .LBB0_160
	v_readlane_b32 s0, v239, 1
	v_readlane_b32 s1, v239, 0
	v_mov_b32 v0, 0
	s_mov_b32 s1, s99
	s_mulk_i32 s0, 0x4800
	s_lshl_b32 s78, s20, 9
	s_add_i32 s25, s0, 0
	s_lshl_b64 s[0:1], s[78:79], 2
	v_readlane_b32 s4, v238, 16
	s_add_u32 s34, s4, s0
	v_readlane_b32 s0, v238, 17
	s_addc_u32 s35, s0, s1
	s_mov_b32 s26, 0
	v_readlane_b32 s23, v238, 28
	v_readlane_b32 s24, v238, 29
	s_branch .LBB0_132

; DI size_t zrowU(int row0, int NT) { return ((size_t)((row0 >> 8) * NT) << 16) + (size_t)((((row0 >> 7) & 1) << 15) | (((row0 >> 5) & 1) << 14) | (((row0 >> 6) & 1) << 11)); }
; #define MFMA32(a, b, c) __builtin_amdgcn_mfma_f32_32x32x16_bf16((a), (b), (c), 0, 0, 0)
; DI void attnB_item(bf16_t* z, int hh, int qs, LAS bf16_t* vs, int lane) {
;     ...
;         const int kpos0 = t < 0 ? 0 : NMETA + 32 * t, kvalid = t < 0 ? NMETA : 32;
;         const int tn = t <= 0 ? -1 : t - 1;
;         const size_t ron = zrowU(tn < 0 ? SEQ : 32 * tn, 32);
;         f32x16 S; bf16x8 qf[8];
; #pragma unroll
;         for (int i = 0; i < 16; ++i) S[i] = 0.f;
; #pragma unroll
;         for (int s = 0; s < 8; ++s) qf[s] = qs_lds[64 * s];
;         asm volatile("s_waitcnt lgkmcnt(0)" ::: "memory"); __builtin_amdgcn_sched_barrier(0);
;         __builtin_amdgcn_s_setprio(1);
; #pragma unroll
;         for (int s = 0; s < 8; ++s) S = MFMA32(kf[s], qf[s], S);
;         __builtin_amdgcn_s_setprio(0);
; #pragma unroll
;         for (int s = 0; s < 8; ++s) kf[s] = *(const bf16x8*)(kbase + ron + (((s >> 1) << 9) | ((s & 1) << 8)));
.LBB0_151:
	s_waitcnt vmcnt(8)
	v_mov_b64_e32 v[148:149], v[144:145]
	v_mov_b64_e32 v[146:147], v[142:143]
	s_cmp_lt_i32 s30, 0
	ds_read_b128 v[66:69], v182 offset:10240
	ds_read_b128 v[142:145], v182 offset:11264
	ds_read_b128 v[150:153], v182 offset:12288
	ds_read_b128 v[192:195], v182 offset:13312
	ds_read_b128 v[196:199], v182 offset:14336
	ds_read_b128 v[200:203], v182 offset:15360
	ds_read_b128 v[204:207], v182 offset:16384
	ds_read_b128 v[208:211], v182 offset:17408
	s_cselect_b64 s[8:9], -1, 0
	s_cmp_gt_i32 s30, -1
	s_cselect_b64 s[4:5], -1, 0
	s_max_i32 s29, s30, 0
	s_add_i32 s29, s29, -1
	s_lshl_b32 s6, s29, 5
	s_cmp_gt_i32 s30, 0
	s_cselect_b32 s10, s6, 0x4000
	s_ashr_i32 s6, s10, 3
	s_lshl_b32 s11, s10, 8
	s_lshl_b32 s31, s10, 9
	s_andn2_b32 s6, s6, 31
	s_and_b32 s11, s11, 0x8000
	s_and_b32 s31, s31, 0x4000
	s_lshl_b32 s10, s10, 5
	s_waitcnt lgkmcnt(0)
	s_ashr_i32 s7, s6, 31
	s_or_b32 s11, s11, s31
	s_and_b32 s10, s10, 0x800
	s_or_b32 s10, s11, s10
	s_lshl_b64 s[6:7], s[6:7], 16
	s_or_b32 s6, s6, s10
	s_waitcnt lgkmcnt(7)
	v_mfma_f32_32x32x16_bf16 v[66:81], v[114:117], v[66:69], 0
	s_cmp_lg_u32 s30, s28
	s_cselect_b64 s[10:11], -1, 0
	s_and_b64 s[38:39], s[10:11], s[4:5]
	s_mov_b64 s[10:11], -1
	v_add_f32_e32 v191, 0, v189
	s_and_b64 vcc, exec, s[38:39]
	s_waitcnt lgkmcnt(6)
	v_mfma_f32_32x32x16_bf16 v[66:81], v[118:121], v[142:145], v[66:81]
	v_lshl_add_u64 v[142:143], s[6:7], 1, v[158:159]
	s_waitcnt lgkmcnt(5)
	v_mfma_f32_32x32x16_bf16 v[66:81], v[122:125], v[150:153], v[66:81]
	s_waitcnt lgkmcnt(4)
	v_mfma_f32_32x32x16_bf16 v[66:81], v[126:129], v[192:195], v[66:81]
	s_waitcnt lgkmcnt(3)
	v_mfma_f32_32x32x16_bf16 v[66:81], v[130:133], v[196:199], v[66:81]
	s_waitcnt lgkmcnt(2)
	v_mfma_f32_32x32x16_bf16 v[66:81], v[134:137], v[200:203], v[66:81]
	global_load_dwordx4 v[114:117], v[142:143], off
	global_load_dwordx4 v[118:121], v[142:143], off offset:512
	global_load_dwordx4 v[122:125], v[142:143], off offset:1024
	global_load_dwordx4 v[126:129], v[142:143], off offset:1536
	global_load_dwordx4 v[130:133], v[142:143], off offset:2048
	global_load_dwordx4 v[134:137], v[142:143], off offset:2560
	s_waitcnt lgkmcnt(1)
	v_mfma_f32_32x32x16_bf16 v[66:81], v[138:141], v[204:207], v[66:81]
	global_load_dwordx4 v[138:141], v[142:143], off offset:3072
	s_nop 0
	global_load_dwordx4 v[142:145], v[142:143], off offset:3584
	s_waitcnt lgkmcnt(0)
	v_mfma_f32_32x32x16_bf16 v[66:81], v[146:149], v[208:211], v[66:81]
	s_nop 11
	v_mul_f32_e32 v207, 0x3e0293ee, v66
	v_mul_f32_e32 v206, 0x3e0293ee, v67
	v_mul_f32_e32 v205, 0x3e0293ee, v68
	v_mul_f32_e32 v204, 0x3e0293ee, v69
	v_mul_f32_e32 v203, 0x3e0293ee, v70
	v_mul_f32_e32 v202, 0x3e0293ee, v71
	v_mul_f32_e32 v201, 0x3e0293ee, v72
	v_mul_f32_e32 v200, 0x3e0293ee, v73
	v_mul_f32_e32 v199, 0x3e0293ee, v74
	v_mul_f32_e32 v198, 0x3e0293ee, v75
	v_mul_f32_e32 v197, 0x3e0293ee, v76
	v_mul_f32_e32 v196, 0x3e0293ee, v77
	v_mul_f32_e32 v195, 0x3e0293ee, v78
	v_mul_f32_e32 v194, 0x3e0293ee, v79
	v_mul_f32_e32 v193, 0x3e0293ee, v80
	v_mul_f32_e32 v192, 0x3e0293ee, v81
	s_cbranch_vccz .LBB0_153
; DI unsigned pk2(float a, float b) { f32x2 v = {a, b}; bf16v2 r = __builtin_convertvector(v, bf16v2); return __builtin_bit_cast(unsigned, r); }
; DI float shflx(float v, int mask, int lane) { return __int_as_float(__builtin_amdgcn_ds_bpermute((lane ^ mask) << 2, __float_as_int(v))); }
; template <bool MASKED>
; DI void attnB_tile_math(const f32x16& S, int kpos0, int kvalid, int qpos, int h, int lane, float& later, unsigned (&pw)[8]) {
;     ...
;     for (int r = 0; r < 16; ++r) {
;         const float x = S[r] * scale2; x2[r] = x;
;         const float e = __builtin_amdgcn_exp2f(-fabsf(x));
;         const float v = fmaxf(x, 0.f) + __builtin_amdgcn_logf(1.0f + e);
;         if (MASKED) { const int row = (r & 3) + 8 * (r >> 2) + 4 * h; const bool vis = (row < kvalid) && (kpos0 + row < qpos); sp[r] = vis ? v : 0.f; }
;         else sp[r] = v;
;     }
;     float G[4], P[4];
; #pragma unroll
;     for (int g = 0; g < 4; ++g) { G[g] = (sp[4 * g] + sp[4 * g + 1]) + (sp[4 * g + 2] + sp[4 * g + 3]); P[g] = shflx(G[g], 32, lane); }
;     float R[4]; R[3] = 0.f; R[2] = G[3] + P[3]; R[1] = R[2] + (G[2] + P[2]); R[0] = R[1] + (G[1] + P[1]);
;     const float total = R[0] + (G[0] + P[0]);
; #pragma unroll
;     for (int g = 0; g < 4; ++g) {
;         float sfx = later + R[g] + (h == 0 ? P[g] : 0.f); float wv[4];
; #pragma unroll
;         for (int i = 3; i >= 0; --i) {
;             const int r = 4 * g + i;
;             sfx += sp[r];
;             float t = __builtin_amdgcn_exp2f(x2[r] - sfx);
;             if (MASKED) { const int row = (r & 3) + 8 * (r >> 2) + 4 * h; const bool vis = (row < kvalid) && (kpos0 + row < qpos); t = vis ? t : 0.f; }
;             wv[i] = t;
;         }
;         pw[2 * g] = pk2(wv[0], wv[1]); pw[2 * g + 1] = pk2(wv[2], wv[3]);
;     }
	v_exp_f32_e64 v147, -|v206|
	v_max_f32_e32 v149, 0, v206
	v_exp_f32_e64 v151, -|v205|
	v_max_f32_e32 v214, 0, v203
	v_add_f32_e32 v147, 1.0, v147
	v_log_f32_e32 v147, v147
	v_max_f32_e32 v215, 0, v202
	v_exp_f32_e64 v148, -|v207|
	v_max_f32_e32 v218, 0, v201
	v_add_f32_e32 v150, v149, v147
	v_exp_f32_e64 v147, -|v204|
	v_add_f32_e32 v149, 1.0, v151
	v_log_f32_e32 v208, v149
	v_exp_f32_e64 v149, -|v203|
	v_add_f32_e32 v147, 1.0, v147
	v_log_f32_e32 v212, v147
	v_exp_f32_e64 v147, -|v202|
	v_add_f32_e32 v149, 1.0, v149
	v_log_f32_e32 v216, v149
	v_exp_f32_e64 v149, -|v200|
	v_add_f32_e32 v147, 1.0, v147
	v_log_f32_e32 v217, v147
	v_exp_f32_e64 v147, -|v201|
	v_add_f32_e32 v148, 1.0, v148
	v_max_f32_e32 v219, 0, v200
	v_pk_add_f32 v[214:215], v[214:215], v[216:217]
	v_add_f32_e32 v147, 1.0, v147
	v_log_f32_e32 v216, v147
	v_add_f32_e32 v147, 1.0, v149
	v_log_f32_e32 v217, v147
	v_exp_f32_e64 v147, -|v199|
	v_exp_f32_e64 v149, -|v198|
	v_log_f32_e32 v148, v148
	v_pk_add_f32 v[216:217], v[218:219], v[216:217]
	v_add_f32_e32 v147, 1.0, v147
	v_log_f32_e32 v220, v147
	v_add_f32_e32 v147, 1.0, v149
	v_exp_f32_e64 v149, -|v197|
	v_log_f32_e32 v224, v147
	v_exp_f32_e64 v147, -|v196|
	v_max_f32_e32 v218, 0, v199
	v_add_f32_e32 v149, 1.0, v149
	v_log_f32_e32 v221, v149
	v_add_f32_e32 v147, 1.0, v147
	v_exp_f32_e64 v149, -|v195|
	v_log_f32_e32 v225, v147
	v_exp_f32_e64 v147, -|v194|
	v_max_f32_e32 v222, 0, v198
	v_add_f32_e32 v149, 1.0, v149
	v_log_f32_e32 v228, v149
	v_add_f32_e32 v147, 1.0, v147
	v_exp_f32_e64 v149, -|v193|
	v_log_f32_e32 v232, v147
	v_exp_f32_e64 v147, -|v192|
	v_max_f32_e32 v219, 0, v197
	v_add_f32_e32 v149, 1.0, v149
	v_log_f32_e32 v229, v149
	v_add_f32_e32 v147, 1.0, v147
	v_log_f32_e32 v233, v147
	v_max_f32_e32 v223, 0, v196
	v_max_f32_e32 v226, 0, v195
	v_max_f32_e32 v230, 0, v194
	v_max_f32_e32 v227, 0, v193
	v_max_f32_e32 v231, 0, v192
	v_pk_add_f32 v[218:219], v[218:219], v[220:221]
	v_pk_add_f32 v[220:221], v[222:223], v[224:225]
	v_pk_add_f32 v[224:225], v[226:227], v[228:229]
	v_pk_add_f32 v[226:227], v[230:231], v[232:233]
	v_pk_add_f32 v[234:235], v[214:215], v[214:215] op_sel_hi:[0,1]
	v_pk_add_f32 v[236:237], v[216:217], v[216:217] op_sel_hi:[0,1]
	v_pk_add_f32 v[222:223], v[218:219], v[220:221]
	v_pk_add_f32 v[228:229], v[224:225], v[226:227]
	v_max_f32_e32 v146, 0, v207
	v_pk_add_f32 v[222:223], v[222:223], v[222:223] op_sel:[0,1] op_sel_hi:[1,0]
	v_pk_add_f32 v[228:229], v[228:229], v[228:229] op_sel:[0,1] op_sel_hi:[1,0]
	v_mov_b32_e32 v147, v235
	v_mov_b32_e32 v149, v237
	ds_bpermute_b32 v209, v184, v222
	ds_bpermute_b32 v213, v184, v228
	v_pk_add_f32 v[146:147], v[146:147], v[148:149]
	ds_bpermute_b32 v151, v184, v147
	v_max_f32_e32 v152, 0, v205
	v_max_f32_e32 v210, 0, v204
	v_mov_b32_e32 v211, v228
	v_mov_b32_e32 v153, v222
	s_waitcnt lgkmcnt(1)
	v_pk_add_f32 v[210:211], v[210:211], v[212:213]
	v_pk_add_f32 v[148:149], v[152:153], v[208:209]
	s_waitcnt lgkmcnt(0)
	v_pk_add_f32 v[222:223], v[146:147], v[150:151]
	v_pk_add_f32 v[152:153], v[148:149], v[210:211]
	v_cndmask_b32_e64 v151, 0, v151, s[36:37]
	v_pk_add_f32 v[222:223], v[222:223], v[152:153]
	ds_bpermute_b32 v208, v184, v222
	v_add_f32_e32 v147, v189, v223
	s_mov_b64 s[10:11], 0
	s_waitcnt lgkmcnt(0)
	v_cndmask_b32_e64 v149, 0, v208, s[36:37]
	v_add_f32_e32 v147, v149, v147
	v_add_f32_e32 v147, v210, v147
	v_fma_f32 v149, v69, s16, -v147
	v_add_f32_e32 v147, v148, v147
	v_fma_f32 v148, v68, s16, -v147
	v_add_f32_e32 v147, v150, v147
	v_fma_f32 v150, v67, s16, -v147
	v_add_f32_e32 v146, v146, v147
	v_add_f32_e32 v147, v189, v153
	v_add_f32_e32 v147, v151, v147
	v_add_f32_e32 v147, v217, v147
	v_fma_f32 v151, v73, s16, -v147
	v_add_f32_e32 v147, v216, v147
	v_fma_f32 v146, v66, s16, -v146
	v_fma_f32 v152, v72, s16, -v147
	v_exp_f32_e32 v149, v149
	v_exp_f32_e32 v148, v148
	v_exp_f32_e32 v150, v150
	v_exp_f32_e32 v146, v146
	v_exp_f32_e32 v151, v151
	v_add_f32_e32 v147, v215, v147
	v_exp_f32_e32 v152, v152
	v_fma_f32 v153, v71, s16, -v147
	v_add_f32_e32 v147, v214, v147
	v_fma_f32 v147, v70, s16, -v147
	v_exp_f32_e32 v153, v153
	v_exp_f32_e32 v210, v147
	v_cvt_pk_bf16_f32 v146, v146, v150
	v_cvt_pk_bf16_f32 v147, v148, v149
	v_cvt_pk_bf16_f32 v149, v152, v151
	v_add_f32_e32 v150, v189, v211
	v_cndmask_b32_e64 v151, 0, v209, s[36:37]
	v_cndmask_b32_e64 v209, 0, v213, s[36:37]
	v_add_f32_e32 v150, v151, v150
	v_add_f32_e32 v209, v191, v209
	v_add_f32_e32 v150, v221, v150
	v_add_f32_e32 v209, v227, v209
	v_cvt_pk_bf16_f32 v148, v210, v153
	v_fma_f32 v151, v77, s16, -v150
	v_add_f32_e32 v150, v219, v150
	v_fma_f32 v210, v81, s16, -v209
	v_add_f32_e32 v209, v225, v209
	v_fma_f32 v152, v76, s16, -v150
	v_add_f32_e32 v150, v220, v150
	v_fma_f32 v211, v80, s16, -v209
	v_add_f32_e32 v209, v226, v209
	v_fma_f32 v153, v75, s16, -v150
	v_add_f32_e32 v150, v218, v150
	v_fma_f32 v212, v79, s16, -v209
	v_add_f32_e32 v209, v224, v209
	v_fma_f32 v150, v74, s16, -v150
	v_fma_f32 v209, v78, s16, -v209
	v_exp_f32_e32 v151, v151
	v_exp_f32_e32 v152, v152
	v_exp_f32_e32 v153, v153
	v_exp_f32_e32 v150, v150
	v_exp_f32_e32 v210, v210
	v_exp_f32_e32 v212, v212
	v_exp_f32_e32 v209, v209
	v_exp_f32_e32 v211, v211
	v_add_f32_e32 v208, v222, v208
	v_cvt_pk_bf16_f32 v150, v150, v153
	v_cvt_pk_bf16_f32 v151, v152, v151
	v_cvt_pk_bf16_f32 v152, v209, v212
	v_cvt_pk_bf16_f32 v153, v211, v210
	v_add_f32_e32 v208, v208, v223

; #define LAS __attribute__((address_space(3)))
; #define MFMA32(a, b, c) __builtin_amdgcn_mfma_f32_32x32x16_bf16((a), (b), (c), 0, 0, 0)
; DI void attnB_item(bf16_t* z, int hh, int qs, LAS bf16_t* vs, int lane) {
;     ...
;         asm volatile("" ::: "memory");
; #pragma unroll
;         for (int i = 0; i < 8; ++i) *(LAS u32x4*)(vs + (16 * (i >> 2) + (lane & 15)) * PB + 32 * (i & 3) + 8 * (lane >> 4)) = vv[i];
; #pragma unroll
;         for (int i = 0; i < 8; ++i) vv[i] = *(const u32x4*)(vbase + ron + (((i >> 2) << 13) | ((i & 3) << 9)));
;         asm volatile("" ::: "memory");
;         bf16x8 af[2][4];
; #pragma unroll
;         for (int s = 0; s < 2; ++s)
; #pragma unroll
;             for (int dt = 0; dt < 4; ++dt) { const LAS bf16_t* lo = vs + trb + 16 * s * PB + 32 * dt; af[s][dt] = tr_frag(lo, lo + 8 * PB); }
;         asm volatile("s_waitcnt lgkmcnt(0)" ::: "memory"); __builtin_amdgcn_sched_barrier(0);
;         __builtin_amdgcn_s_setprio(1);
; #pragma unroll
;         for (int s = 0; s < 2; ++s) {
;             const u32x4 pwv = {pw[4 * s], pw[4 * s + 1], pw[4 * s + 2], pw[4 * s + 3]};
;             const bf16x8 bfrag = __builtin_bit_cast(bf16x8, pwv);
; #pragma unroll
;             for (int dt = 0; dt < 4; ++dt) acc[dt] = MFMA32(af[s][dt], bfrag, acc[dt]);
;         }
;         __builtin_amdgcn_s_setprio(0);
;         if (t < 0) break;
;         if (__all(later > 150.1f)) break;
.LBB0_155:
	s_waitcnt vmcnt(15)
	ds_write_b128 v188, v[82:85]
	s_waitcnt vmcnt(14)
	ds_write_b128 v188, v[86:89] offset:64
	s_waitcnt vmcnt(13)
	ds_write_b128 v188, v[90:93] offset:128
	s_waitcnt vmcnt(12)
	ds_write_b128 v188, v[94:97] offset:192
	s_waitcnt vmcnt(11)
	ds_write_b128 v188, v[98:101] offset:5120
	s_waitcnt vmcnt(10)
	ds_write_b128 v188, v[102:105] offset:5184
	s_waitcnt vmcnt(9)
	ds_write_b128 v188, v[106:109] offset:5248
	s_waitcnt vmcnt(8)
	ds_write_b128 v188, v[110:113] offset:5312
	v_lshl_add_u64 v[66:67], s[6:7], 1, v[160:161]
	global_load_dwordx4 v[82:85], v[66:67], off
	global_load_dwordx4 v[86:89], v[66:67], off offset:1024
	global_load_dwordx4 v[90:93], v[66:67], off offset:2048
	global_load_dwordx4 v[94:97], v[66:67], off offset:3072
	v_add_co_u32_e32 v66, vcc, s3, v66
	s_nop 1
	v_addc_co_u32_e32 v67, vcc, 0, v67, vcc
	global_load_dwordx4 v[98:101], v[66:67], off
	global_load_dwordx4 v[102:105], v[66:67], off offset:1024
	global_load_dwordx4 v[106:109], v[66:67], off offset:2048
	global_load_dwordx4 v[110:113], v[66:67], off offset:3072
	ds_read_b64_tr_b16 v[66:67], v190
	ds_read_b64_tr_b16 v[70:71], v190 offset:64
	ds_read_b64_tr_b16 v[74:75], v190 offset:128
	ds_read_b64_tr_b16 v[78:79], v190 offset:192
	ds_read_b64_tr_b16 v[68:69], v190 offset:2560
	ds_read_b64_tr_b16 v[72:73], v190 offset:2624
	ds_read_b64_tr_b16 v[76:77], v190 offset:2688
	ds_read_b64_tr_b16 v[80:81], v190 offset:2752
	ds_read_b64_tr_b16 v[192:193], v190 offset:5120
	ds_read_b64_tr_b16 v[196:197], v190 offset:5184
	ds_read_b64_tr_b16 v[200:201], v190 offset:5248
	ds_read_b64_tr_b16 v[204:205], v190 offset:5312
	ds_read_b64_tr_b16 v[194:195], v190 offset:7680
	ds_read_b64_tr_b16 v[198:199], v190 offset:7744
	ds_read_b64_tr_b16 v[202:203], v190 offset:7808
	ds_read_b64_tr_b16 v[206:207], v190 offset:7872
	s_waitcnt lgkmcnt(0)
	s_waitcnt lgkmcnt(11)
	v_mfma_f32_32x32x16_bf16 v[50:65], v[66:69], v[146:149], v[50:65]
	s_waitcnt lgkmcnt(10)
	v_mfma_f32_32x32x16_bf16 v[34:49], v[70:73], v[146:149], v[34:49]
	s_waitcnt lgkmcnt(9)
	v_mfma_f32_32x32x16_bf16 v[18:33], v[74:77], v[146:149], v[18:33]
	s_waitcnt lgkmcnt(8)
	v_mfma_f32_32x32x16_bf16 v[2:17], v[78:81], v[146:149], v[2:17]
	s_waitcnt lgkmcnt(3)
	v_mfma_f32_32x32x16_bf16 v[50:65], v[192:195], v[150:153], v[50:65]
	s_waitcnt lgkmcnt(2)
	v_mfma_f32_32x32x16_bf16 v[34:49], v[196:199], v[150:153], v[34:49]
	s_waitcnt lgkmcnt(1)
	v_mfma_f32_32x32x16_bf16 v[18:33], v[200:203], v[150:153], v[18:33]
	s_waitcnt lgkmcnt(0)
	v_mfma_f32_32x32x16_bf16 v[2:17], v[204:207], v[150:153], v[2:17]
	s_andn2_b64 vcc, exec, s[4:5]
	s_mov_b64 s[4:5], -1
	s_cbranch_vccnz .LBB0_150
	v_add_f32_e32 v189, v189, v208
	s_mov_b32 s4, 0x4306199a
	v_cmp_lt_f32_e32 vcc, s4, v189
	s_cmp_eq_u64 vcc, exec
	s_cselect_b64 s[4:5], -1, 0
	s_branch .LBB0_150

; template <bool MASKED>
; DI bool attnA_tile_math(const f32x16& Su, const LAS float* bt, int qpos, int kpos0, int kvalid, bool meta_tile, int h, int lane, float& m, float& l, float& corr, bf16x8 (&bfrag)[2]) {
;     float sc[16]; float tmax = -1e30f;
; #pragma unroll
;     for (int r = 0; r < 16; ++r) {
;         const int row = (r & 3) + 8 * (r >> 2) + 4 * h;
;         const int dist = qpos - (kpos0 + row);
;         if (MASKED) {
;             const bool vis = (row < kvalid) && (dist >= 0) && (meta_tile || dist < 128);
;             const int di = dist < 0 ? 0 : (dist > 128 ? 128 : dist);
;             const float v = Su[r] * (0.125f * 1.4426950408889634f) + bt[di];
;             sc[r] = vis ? v : -1e30f;
;         } else sc[r] = Su[r] * (0.125f * 1.4426950408889634f) + bt[dist];
;         tmax = fmaxf(tmax, sc[r]);
;     }
;     tmax = fmaxf(tmax, shflx(tmax, 32, lane));
;     const bool resc = __any(tmax > m + 16.0f);
;     float mnew = m; corr = 1.0f;
;     if (resc) { mnew = fmaxf(m, tmax); corr = __builtin_amdgcn_exp2f(m - mnew); }
;     float pr[16]; float psum = 0.f;
; #pragma unroll
;     for (int r = 0; r < 16; ++r) { pr[r] = __builtin_amdgcn_exp2f(sc[r] - mnew); psum += pr[r]; }
;     psum += shflx(psum, 32, lane);
; DI void attnA_item(bf16_t* z, const float* sinks, int hp, int qs, LAS bf16_t* vs, const LAS float* btab, int lane) {
;     ...
;             f32x16 Su; bf16x8 qf[4];
; #pragma unroll
;             for (int i = 0; i < 16; ++i) Su[i] = 0.f;
; #pragma unroll
;             for (int s = 0; s < 4; ++s) qf[s] = qs_lds[64 * (4 * u + s)];
;             asm volatile("s_waitcnt lgkmcnt(0)" ::: "memory"); __builtin_amdgcn_sched_barrier(0);
;             __builtin_amdgcn_s_setprio(1);
; #pragma unroll
;             for (int s = 0; s < 4; ++s) Su = MFMA32(kf[s], qf[s], Su);
;             __builtin_amdgcn_s_setprio(0);
;             if (u == 1) {
; #pragma unroll
;                 for (int s = 0; s < 4; ++s) kf[s] = *(const bf16x8*)(kbase + ron + (((s >> 1) << 9) | ((s & 1) << 8)));
;             }
;             const LAS float* bt = btab + (2 * hp + u) * 129;
;             float corr; bool resc;
;             if (interior) resc = attnA_tile_math<false>(Su, bt, qpos, kpos0, kvalid, t < 0, h, lane, m[u], l[u], corr, bfrag[u]);
;             else resc = attnA_tile_math<true>(Su, bt, qpos, kpos0, kvalid, t < 0, h, lane, m[u], l[u], corr, bfrag[u]);
.LqkA:
	s_waitcnt vmcnt(7) lgkmcnt(3)
	v_mfma_f32_32x32x16_bf16 v[66:81], v[94:97], v[66:69], 0
	s_waitcnt vmcnt(6) lgkmcnt(2)
	v_mfma_f32_32x32x16_bf16 v[66:81], v[90:93], v[120:123], v[66:81]
	s_waitcnt vmcnt(5) lgkmcnt(1)
	v_mfma_f32_32x32x16_bf16 v[66:81], v[86:89], v[168:171], v[66:81]
	s_waitcnt vmcnt(4) lgkmcnt(0)
	v_mfma_f32_32x32x16_bf16 v[66:81], v[82:85], v[178:181], v[66:81]
	s_nop 10
	v_mul_f32_e32 v66, 0x3e38aa3b, v66
	s_mov_b64 s[10:11], -1
	s_and_b64 vcc, exec, s[6:7]
	v_add_f32_e32 v207, 0x41800000, v118
	v_max_f32_e32 v206, v118, v118
	s_cbranch_vccz .LBB0_199
	v_lshl_add_u32 v204, v0, 2, s87
	v_lshl_add_u32 v203, v173, 2, s87
	v_lshl_add_u32 v202, v182, 2, s87
	v_lshl_add_u32 v201, v183, 2, s87
	v_lshl_add_u32 v200, v184, 2, s87
	v_lshl_add_u32 v199, v185, 2, s87
	v_lshl_add_u32 v198, v187, 2, s87
	v_lshl_add_u32 v197, v188, 2, s87
	v_lshl_add_u32 v196, v189, 2, s87
	v_lshl_add_u32 v195, v190, 2, s87
	v_lshl_add_u32 v194, v191, 2, s87
	v_lshl_add_u32 v193, v192, 2, s87
	v_lshl_add_u32 v192, v205, 2, s87
	v_lshl_add_u32 v191, v215, 2, s87
	v_lshl_add_u32 v190, v216, 2, s87
	v_lshl_add_u32 v189, v217, 2, s87
	ds_read_b32 v0, v204
	ds_read_b32 v120, v203
	ds_read_b32 v121, v202
	ds_read_b32 v122, v201
	ds_read_b32 v123, v200
	ds_read_b32 v168, v199
	ds_read_b32 v169, v198
	ds_read_b32 v170, v197
	s_waitcnt lgkmcnt(7)
	v_add_f32_e32 v0, v66, v0
	s_waitcnt lgkmcnt(6)
	v_fmac_f32_e32 v120, 0x3e38aa3b, v67
	v_cndmask_b32_e64 v171, v177, v0, s[36:37]
	v_cndmask_b32_e64 v120, v177, v120, s[38:39]
	s_waitcnt lgkmcnt(5)
	v_fmac_f32_e32 v121, 0x3e38aa3b, v68
	s_waitcnt lgkmcnt(4)
	v_fmac_f32_e32 v122, 0x3e38aa3b, v69
	s_waitcnt lgkmcnt(3)
	v_fmac_f32_e32 v123, 0x3e38aa3b, v70
	s_waitcnt lgkmcnt(2)
	v_fmac_f32_e32 v168, 0x3e38aa3b, v71
	s_waitcnt lgkmcnt(1)
	v_fmac_f32_e32 v169, 0x3e38aa3b, v72
	s_waitcnt lgkmcnt(0)
	v_fmac_f32_e32 v170, 0x3e38aa3b, v73
	v_max3_f32 v0, v171, s18, v120
	v_cndmask_b32_e64 v173, v177, v121, s[40:41]
	v_cndmask_b32_e64 v122, v177, v122, s[44:45]
	v_cndmask_b32_e64 v178, v177, v123, s[48:49]
	v_cndmask_b32_e64 v179, v177, v168, s[52:53]
	v_cndmask_b32_e64 v180, v177, v169, s[56:57]
	v_cndmask_b32_e64 v181, v177, v170, s[60:61]
	ds_read_b32 v121, v196
	ds_read_b32 v123, v195
	ds_read_b32 v168, v194
	ds_read_b32 v169, v193
	ds_read_b32 v170, v192
	ds_read_b32 v182, v191
	ds_read_b32 v183, v190
	ds_read_b32 v184, v189
	v_max3_f32 v0, v0, v173, v122
	v_max3_f32 v0, v0, v178, v179
	s_waitcnt lgkmcnt(7)
	v_fmac_f32_e32 v121, 0x3e38aa3b, v74
	s_waitcnt lgkmcnt(6)
	v_fmac_f32_e32 v123, 0x3e38aa3b, v75
	v_max3_f32 v0, v0, v180, v181
	v_cndmask_b32_e64 v185, v177, v121, s[42:43]
	v_cndmask_b32_e64 v187, v177, v123, s[46:47]
	s_waitcnt lgkmcnt(5)
	v_fmac_f32_e32 v168, 0x3e38aa3b, v76
	s_waitcnt lgkmcnt(4)
	v_fmac_f32_e32 v169, 0x3e38aa3b, v77
	v_max3_f32 v0, v0, v185, v187
	v_cndmask_b32_e64 v188, v177, v168, s[50:51]
	v_cndmask_b32_e64 v205, v177, v169, s[54:55]
	s_waitcnt lgkmcnt(3)
	v_fmac_f32_e32 v170, 0x3e38aa3b, v78
	s_waitcnt lgkmcnt(2)
	v_fmac_f32_e32 v182, 0x3e38aa3b, v79
	v_max3_f32 v0, v0, v188, v205
	v_cndmask_b32_e64 v215, v177, v170, s[58:59]
	v_cndmask_b32_e64 v216, v177, v182, s[62:63]
	s_waitcnt lgkmcnt(1)
	v_fmac_f32_e32 v183, 0x3e38aa3b, v80
	s_waitcnt lgkmcnt(0)
	v_fmac_f32_e32 v184, 0x3e38aa3b, v81
	v_max3_f32 v0, v0, v215, v216
	v_cndmask_b32_e64 v217, v177, v183, s[64:65]
	v_cndmask_b32_e64 v218, v177, v184, s[66:67]
	v_max3_f32 v0, v0, v217, v218
	ds_bpermute_b32 v121, v145, v0
	s_mov_b64 s[10:11], 0
	s_waitcnt lgkmcnt(0)
	v_max_f32_e32 v121, v121, v121
	v_max_f32_e32 v0, v0, v121
	v_max_f32_e32 v121, v206, v0
	v_sub_f32_e32 v123, v118, v121
	v_exp_f32_e32 v123, v123
	v_cmp_gt_f32_e32 vcc, v0, v207
	s_cmp_lg_u64 vcc, 0
	s_cselect_b64 s[4:5], -1, 0
	v_cndmask_b32_e64 v121, v118, v121, s[4:5]
	v_cndmask_b32_e64 v0, 1.0, v123, s[4:5]
	v_sub_f32_e32 v123, v171, v121
	v_exp_f32_e32 v123, v123
	v_sub_f32_e32 v120, v120, v121
	v_exp_f32_e32 v168, v120
	v_sub_f32_e32 v120, v173, v121
	v_exp_f32_e32 v169, v120
	v_sub_f32_e32 v120, v122, v121
	v_exp_f32_e32 v122, v120
	v_add_f32_e32 v120, 0, v123
	v_add_f32_e32 v120, v168, v120
	v_add_f32_e32 v120, v169, v120
	v_add_f32_e32 v182, v122, v120
	v_sub_f32_e32 v120, v178, v121
	v_exp_f32_e32 v170, v120
	v_sub_f32_e32 v120, v179, v121
	v_exp_f32_e32 v120, v120
	v_sub_f32_e32 v171, v180, v121
	v_exp_f32_e32 v171, v171
	v_sub_f32_e32 v173, v181, v121
	v_exp_f32_e32 v173, v173
	v_add_f32_e32 v178, v170, v182
	v_add_f32_e32 v178, v120, v178
	v_add_f32_e32 v178, v171, v178
	v_add_f32_e32 v182, v173, v178
	v_sub_f32_e32 v178, v185, v121
	v_exp_f32_e32 v178, v178
	v_sub_f32_e32 v179, v187, v121
	v_exp_f32_e32 v179, v179
	v_sub_f32_e32 v180, v188, v121
	v_exp_f32_e32 v180, v180
	v_sub_f32_e32 v181, v205, v121
	v_exp_f32_e32 v181, v181
	v_add_f32_e32 v182, v178, v182
	v_add_f32_e32 v182, v179, v182
	v_add_f32_e32 v182, v180, v182
	v_add_f32_e32 v187, v181, v182
	v_sub_f32_e32 v182, v215, v121
	v_exp_f32_e32 v182, v182
	v_sub_f32_e32 v183, v216, v121
	v_exp_f32_e32 v183, v183
	v_sub_f32_e32 v184, v217, v121
	v_exp_f32_e32 v184, v184
	v_sub_f32_e32 v185, v218, v121
	v_exp_f32_e32 v185, v185
	v_add_f32_e32 v187, v182, v187
	v_add_f32_e32 v187, v183, v187
	v_add_f32_e32 v187, v184, v187
	v_add_f32_e32 v187, v185, v187
	ds_bpermute_b32 v188, v145, v187

; DI size_t zrowU(int row0, int NT) { return ((size_t)((row0 >> 8) * NT) << 16) + (size_t)((((row0 >> 7) & 1) << 15) | (((row0 >> 5) & 1) << 14) | (((row0 >> 6) & 1) << 11)); }
; #define MFMA32(a, b, c) __builtin_amdgcn_mfma_f32_32x32x16_bf16((a), (b), (c), 0, 0, 0)
; DI void attnA_item(bf16_t* z, const float* sinks, int hp, int qs, LAS bf16_t* vs, const LAS float* btab, int lane) {
;     ...
;         const int kpos0 = t < 0 ? 0 : NMETA + 32 * t, kvalid = t < 0 ? NMETA : 32;
;         const bool lastt = metaq || t == thi;
;         const bool interior = !metaq && t >= 0 && t > qs - 4 && t < qs;
;         const int tn = lastt ? t : (t < 0 ? tlo : t + 1);
;         const size_t ron = zrowU(tn < 0 ? SEQ : 32 * tn, 18);
;         bf16x8 bfrag[2][2];
; #pragma unroll
;         for (int u = 0; u < 2; ++u) {
;             f32x16 Su; bf16x8 qf[4];
; #pragma unroll
;             for (int i = 0; i < 16; ++i) Su[i] = 0.f;
; #pragma unroll
;             for (int s = 0; s < 4; ++s) qf[s] = qs_lds[64 * (4 * u + s)];
;             asm volatile("s_waitcnt lgkmcnt(0)" ::: "memory"); __builtin_amdgcn_sched_barrier(0);
;             __builtin_amdgcn_s_setprio(1);
; #pragma unroll
;             for (int s = 0; s < 4; ++s) Su = MFMA32(kf[s], qf[s], Su);
;             __builtin_amdgcn_s_setprio(0);
;             if (u == 1) {
; #pragma unroll
;                 for (int s = 0; s < 4; ++s) kf[s] = *(const bf16x8*)(kbase + ron + (((s >> 1) << 9) | ((s & 1) << 8)));
.LBB0_203:
	s_cmp_eq_u32 s31, s29
	s_cselect_b64 s[4:5], -1, 0
	s_or_b64 s[4:5], s[68:69], s[4:5]
	s_add_i32 s10, s31, 1
	s_and_b64 s[8:9], s[8:9], exec
	s_cselect_b32 s30, s78, s10
	s_and_b64 s[8:9], s[4:5], exec
	s_cselect_b32 s8, s31, s30
	s_lshl_b32 s9, s8, 5
	s_cmp_gt_i32 s8, -1
	s_cselect_b32 s10, s9, 0x4000
	ds_read_b128 v[66:69], v129 offset:10240
	ds_read_b128 v[206:209], v129 offset:11264
	ds_read_b128 v[210:213], v129 offset:12288
	ds_read_b128 v[214:217], v129 offset:13312
	s_ashr_i32 s8, s10, 8
	s_lshl_b32 s11, s10, 8
	s_lshl_b32 s31, s10, 9
	s_mul_i32 s8, s8, 18
	s_and_b32 s11, s11, 0x8000
	s_and_b32 s31, s31, 0x4000
	s_lshl_b32 s10, s10, 5
	s_ashr_i32 s9, s8, 31
	s_or_b32 s11, s11, s31
	s_and_b32 s10, s10, 0x800
	s_lshl_b64 s[8:9], s[8:9], 16
	s_or_b32 s10, s11, s10
	s_waitcnt lgkmcnt(0)
	s_or_b32 s8, s8, s10
	v_lshl_add_u64 v[218:219], s[8:9], 1, v[114:115]
	s_waitcnt lgkmcnt(3)
	v_mfma_f32_32x32x16_bf16 v[66:81], v[94:97], v[66:69], 0
	s_waitcnt lgkmcnt(2)
	v_mfma_f32_32x32x16_bf16 v[66:81], v[90:93], v[206:209], v[66:81]
	s_waitcnt lgkmcnt(1)
	v_mfma_f32_32x32x16_bf16 v[66:81], v[86:89], v[210:213], v[66:81]
	s_waitcnt lgkmcnt(0)
	v_mfma_f32_32x32x16_bf16 v[66:81], v[82:85], v[214:217], v[66:81]
	global_load_dwordx4 v[94:97], v[218:219], off
	global_load_dwordx4 v[90:93], v[218:219], off offset:512
	global_load_dwordx4 v[86:89], v[218:219], off offset:1024
	global_load_dwordx4 v[82:85], v[218:219], off offset:1536
	s_nop 6
	v_mul_f32_e32 v220, 0x3e38aa3b, v66
	s_mov_b64 s[10:11], -1
	s_andn2_b64 vcc, exec, s[6:7]
	v_add_f32_e32 v207, 0x41800000, v119
	v_max_f32_e32 v118, v119, v119
	s_cbranch_vccz .LBB0_209
	s_andn2_b64 vcc, exec, s[10:11]
	s_cbranch_vccz .LBB0_210

; #define LAS __attribute__((address_space(3)))
; #define MFMA32(a, b, c) __builtin_amdgcn_mfma_f32_32x32x16_bf16((a), (b), (c), 0, 0, 0)
; DI void attnA_item(bf16_t* z, const float* sinks, int hp, int qs, LAS bf16_t* vs, const LAS float* btab, int lane) {
;     ...
;         asm volatile("" ::: "memory");
; #pragma unroll
;         for (int i = 0; i < 4; ++i) *(LAS u32x4*)(vs + (16 * (i >> 1) + (lane & 15)) * PA + 32 * (i & 1) + 8 * (lane >> 4)) = vv[i];
; #pragma unroll
;         for (int i = 0; i < 4; ++i) vv[i] = *(const u32x4*)(vbase + ron + (((i >> 1) << 13) | ((i & 1) << 9)));
;         asm volatile("" ::: "memory");
;         bf16x8 af[2][2];
; #pragma unroll
;         for (int s = 0; s < 2; ++s)
; #pragma unroll
;             for (int dt = 0; dt < 2; ++dt) { const LAS bf16_t* lo = vs + trb + 16 * s * PA + 32 * dt; af[s][dt] = tr_frag(lo, lo + 8 * PA); }
;         asm volatile("s_waitcnt lgkmcnt(0)" ::: "memory"); __builtin_amdgcn_sched_barrier(0);
;         __builtin_amdgcn_s_setprio(1);
; #pragma unroll
;         for (int s = 0; s < 2; ++s)
; #pragma unroll
;             for (int dt = 0; dt < 2; ++dt) {
;                 acc[0][dt] = MFMA32(af[s][dt], bfrag[0][s], acc[0][dt]);
;                 acc[1][dt] = MFMA32(af[s][dt], bfrag[1][s], acc[1][dt]);
;             }
;         __builtin_amdgcn_s_setprio(0);
;         if (lastt) break;
;         t = tn;
.LBB0_207:
	s_waitcnt vmcnt(7)
	ds_write_b128 v164, v[98:101]
	s_waitcnt vmcnt(6)
	ds_write_b128 v164, v[102:105] offset:64
	s_waitcnt vmcnt(5)
	ds_write_b128 v164, v[106:109] offset:3072
	s_waitcnt vmcnt(4)
	ds_write_b128 v164, v[110:113] offset:3136
	v_lshl_add_u64 v[80:81], s[8:9], 1, v[116:117]
	global_load_dwordx4 v[98:101], v[80:81], off
	global_load_dwordx4 v[102:105], v[80:81], off offset:1024
	v_add_co_u32_e32 v80, vcc, s3, v80
	s_waitcnt lgkmcnt(4)
	v_add_f32_e32 v74, v225, v226
	v_addc_co_u32_e32 v81, vcc, 0, v81, vcc
	global_load_dwordx4 v[106:109], v[80:81], off
	global_load_dwordx4 v[110:113], v[80:81], off offset:1024
	v_add_f32_e32 v75, v187, v188
	v_fmac_f32_e32 v74, v167, v66
	v_fmac_f32_e32 v75, v166, v0
	v_cvt_pk_bf16_f32 v76, v123, v168
	v_cvt_pk_bf16_f32 v77, v169, v122
	v_cvt_pk_bf16_f32 v166, v178, v179
	v_cvt_pk_bf16_f32 v167, v180, v181
	v_cvt_pk_bf16_f32 v168, v182, v183
	v_cvt_pk_bf16_f32 v169, v184, v185
	ds_read_b64_tr_b16 v[178:179], v165
	ds_read_b64_tr_b16 v[180:181], v165 offset:1536
	ds_read_b64_tr_b16 v[182:183], v165 offset:64
	ds_read_b64_tr_b16 v[184:185], v165 offset:1600
	ds_read_b64_tr_b16 v[186:187], v165 offset:3072
	ds_read_b64_tr_b16 v[188:189], v165 offset:4608
	ds_read_b64_tr_b16 v[190:191], v165 offset:3136
	ds_read_b64_tr_b16 v[192:193], v165 offset:4672
	s_waitcnt lgkmcnt(0)
	v_cvt_pk_bf16_f32 v70, v208, v209
	v_cvt_pk_bf16_f32 v71, v210, v211
	v_cvt_pk_bf16_f32 v72, v212, v213
	v_cvt_pk_bf16_f32 v73, v214, v215
	v_cvt_pk_bf16_f32 v66, v216, v217
	v_cvt_pk_bf16_f32 v67, v218, v219
	v_cvt_pk_bf16_f32 v68, v221, v222
	v_cvt_pk_bf16_f32 v69, v223, v224
	v_cvt_pk_bf16_f32 v78, v170, v120
	v_cvt_pk_bf16_f32 v79, v171, v173
	s_waitcnt lgkmcnt(6)
	v_mfma_f32_32x32x16_bf16 v[50:65], v[178:181], v[76:79], v[50:65]
	v_mfma_f32_32x32x16_bf16 v[18:33], v[178:181], v[70:73], v[18:33]
	s_waitcnt lgkmcnt(4)
	v_mfma_f32_32x32x16_bf16 v[34:49], v[182:185], v[76:79], v[34:49]
	v_mfma_f32_32x32x16_bf16 v[2:17], v[182:185], v[70:73], v[2:17]
	s_waitcnt lgkmcnt(2)
	v_mfma_f32_32x32x16_bf16 v[50:65], v[186:189], v[166:169], v[50:65]
	v_mfma_f32_32x32x16_bf16 v[18:33], v[186:189], v[66:69], v[18:33]
	s_waitcnt lgkmcnt(0)
	v_mfma_f32_32x32x16_bf16 v[34:49], v[190:193], v[166:169], v[34:49]
	v_mfma_f32_32x32x16_bf16 v[2:17], v[190:193], v[66:69], v[2:17]
	s_andn2_b64 vcc, exec, s[4:5]
	s_cbranch_vccz .LBB0_211
	v_mov_b32_e32 v167, v74
	v_mov_b32_e32 v166, v75
	s_mov_b32 s31, s30
	v_mov_b32_e32 v118, v121
	v_mov_b32_e32 v119, v206
	s_branch .LBB0_197

; DI int lane_id_fresh() { unsigned zero; asm volatile("v_mov_b32 %0, 0" : "=v"(zero)); return (int)__builtin_amdgcn_mbcnt_hi(~0u, __builtin_amdgcn_mbcnt_lo(~0u, zero)); }
; DI void xcd_barrier(const XcdBarrier& b, int wave_s) {
;     asm volatile("s_waitcnt vmcnt(0)" ::: "memory");
;     __syncthreads();
;     if (wave_s == 0 && lane_id_fresh() == 0) {
;         unsigned* bar = b.bar;
;         __builtin_amdgcn_s_waitcnt(0);
;         unsigned nloc = b.st[0], nx = b.st[1];
;         if (nloc == 0u) { xcd_barrier_complete(bar, b.x, nloc, nx); b.st[0] = nloc; b.st[1] = nx; }
.LBB0_214:
	s_setprio 0
	s_waitcnt vmcnt(0)
	v_readlane_b32 s0, v238, 26
	v_readlane_b32 s1, v238, 27
	s_and_b64 vcc, exec, s[0:1]
	s_barrier
	s_cbranch_vccnz .LBB0_268
	v_mov_b32 v0, 0
	s_nop 0
	v_mbcnt_lo_u32_b32 v0, -1, v0
	v_mbcnt_hi_u32_b32 v0, -1, v0
	v_cmp_eq_u32_e32 vcc, 0, v0
	s_and_saveexec_b64 s[0:1], vcc
	s_cbranch_execz .LBB0_267
	v_readlane_b32 s4, v238, 20
	s_waitcnt vmcnt(0) expcnt(0) lgkmcnt(0)
	s_nop 0
	v_mov_b32_e32 v0, s4
	ds_read_b32 v3, v0
	v_readlane_b32 s4, v238, 21
	s_waitcnt lgkmcnt(0)
	v_cmp_ne_u32_e32 vcc, 0, v3
	v_mov_b32_e32 v0, s4
	ds_read_b32 v2, v0
	s_cbranch_vccnz .LBB0_231
	s_mov_b32 s10, 1
	s_branch .LBB0_219
